# speedup vs baseline: 1.0098x; 1.0098x over previous
; #define WAIT_V(n) asm volatile("s_waitcnt vmcnt(%0)" ::"n"(n) : "memory")
; #define COMPUTE(buf) do { _Pragma("unroll") for (int ks = 0; ks < KS; ++ks) KSTEP(buf, ks); } while (0)
; __device__ __forceinline__ void gemm_tile(const TileDesc& d, const TileDesc& dn, bool has_next, bool k0_pending) {
;   const bf16* __restrict__ Ab = d.A; const bf16* __restrict__ Bb = d.B; const int lda = d.lda, ldb = d.ldb, K = d.K;
;   int tid = threadIdx.x;
;   asm volatile("" : "+v"(tid));
;   const int wid = tid >> 6, lane = tid & 63, wr = wid >> 2, wc = wid & 3, fr = lane & 15, fq = lane >> 4;
;   int r0, c0; stage_rc(wid * 1024 + lane * 16, r0, c0);
;   const unsigned voA = (unsigned)(r0 * lda + c0), voB = (unsigned)(r0 * ldb + c0);
;   const unsigned nvoA = (unsigned)(r0 * dn.lda + c0), nvoB = (unsigned)(r0 * dn.ldb + c0);
;   const int wbase = __builtin_amdgcn_readfirstlane(wid) * 1024;
;   f32x4 acc[8][4];
; #pragma unroll
;   for (int m = 0; m < 8; ++m)
; #pragma unroll
;     for (int n = 0; n < 4; ++n) acc[m][n] = f32x4{0.f, 0.f, 0.f, 0.f};
;   const int fo0 = fr * 128 + ((fq ^ ((fr >> 1) & 7)) << 4), fo1 = fo0 ^ 64;
;   const char* aF = g_shm + wr * 16384;
;   const char* bF = g_shm + TILE_B + wc * 8192;
;     ...
;   const int nt = K / BK;
;   const bool pf_in_loop = has_next && d.kind != EPI_GATE;
;   if (k0_pending) { WAIT_V(0); __syncthreads(); }
;   for (int t = 0; t < nt - 1; ++t) { int cur = t & 1;
;     GLDS_STAGE_OF(Ab, lda, Bb, ldb, voA, voB, cur ^ 1, t + 1);
;     COMPUTE(cur);
;     WAIT_V(0); __syncthreads(); }
.LBB0_387:
	v_and_b32_e32 v148, 63, v0
	v_lshlrev_b32_e32 v2, 4, v148
	v_lshl_or_b32 v2, v1, 10, v2
	v_ashrrev_i32_e32 v146, 7, v2
	v_lshrrev_b32_e32 v2, 8, v2
	s_waitcnt lgkmcnt(0)
	s_lshl_b32 s38, s16, 10
	s_ashr_i32 s16, s53, 31
	v_xor_b32_e32 v2, v2, v0
	s_lshr_b32 s16, s16, 26
	v_lshlrev_b32_e32 v2, 3, v2
	s_add_i32 s16, s53, s16
	v_and_b32_e32 v195, 3, v1
	v_bfe_u32 v193, v0, 4, 2
	v_and_b32_e32 v128, 56, v2
	v_lshrrev_b32_e32 v1, 1, v0
	s_ashr_i32 s16, s16, 6
	v_ashrrev_i32_e32 v194, 8, v0
	v_and_b32_e32 v165, 15, v0
	v_mad_u64_u32 v[2:3], s[18:19], v146, s83, v[128:129]
	v_mad_u64_u32 v[4:5], s[18:19], v146, s59, v[128:129]
	v_bfe_u32 v149, v0, 1, 3
	v_bitop3_b32 v0, v193, v1, 7 bitop3:0x78
	s_max_i32 s16, s16, 2
	v_lshlrev_b32_e32 v150, 7, v165
	v_lshlrev_b32_e32 v0, 4, v0
	v_mov_b32_e32 v3, v164
	v_mov_b32_e32 v5, v164
	s_lshl_b32 s54, s83, 7
	s_lshl_b32 s60, s59, 7
	s_mul_i32 s62, s83, 0xc0
	s_mul_i32 s76, s59, 0xc0
	s_add_i32 s39, s16, -1
	s_lshl_b32 s16, s59, 6
	s_lshl_b32 s17, s83, 6
	v_or_b32_e32 v152, v0, v150
	v_bitop3_b32 v129, v0, 64, v150 bitop3:0x36
	v_lshlrev_b64 v[0:1], 1, v[2:3]
	v_lshlrev_b64 v[2:3], 1, v[4:5]
	s_ashr_i32 s55, s54, 31
	s_ashr_i32 s61, s60, 31
	s_ashr_i32 s63, s62, 31
	s_ashr_i32 s77, s76, 31
	s_add_i32 s16, s16, 64
	s_add_i32 s18, s17, 64
	v_lshl_add_u64 v[132:133], s[34:35], 0, v[2:3]
	s_add_u32 s34, s34, 0x80
	s_addc_u32 s35, s35, 0
	s_lshl_b64 s[76:77], s[76:77], 1
	s_add_u32 s76, s34, s76
	s_addc_u32 s77, s35, s77
	v_lshl_add_u64 v[130:131], s[56:57], 0, v[0:1]
	s_add_u32 s56, s56, 0x80
	s_addc_u32 s57, s57, 0
	s_lshl_b64 s[62:63], s[62:63], 1
	s_add_u32 s62, s56, s62
	s_addc_u32 s63, s57, s63
	s_lshl_b64 s[60:61], s[60:61], 1
	s_add_u32 s60, s34, s60
	s_addc_u32 s61, s35, s61
	s_lshl_b64 s[54:55], s[54:55], 1
	s_add_u32 s54, s56, s54
	s_addc_u32 s55, s57, s55
	v_lshl_add_u64 v[136:137], s[62:63], 0, v[0:1]
	v_lshl_add_u64 v[140:141], s[54:55], 0, v[0:1]
	v_lshl_add_u64 v[144:145], s[56:57], 0, v[0:1]
	v_mov_b32_e32 v0, 0
	v_lshlrev_b32_e32 v151, 14, v194
	v_lshlrev_b32_e32 v153, 13, v195
	v_lshl_add_u64 v[134:135], s[76:77], 0, v[2:3]
	v_lshl_add_u64 v[138:139], s[60:61], 0, v[2:3]
	v_lshl_add_u64 v[142:143], s[34:35], 0, v[2:3]
	s_mov_b32 s43, 0
	s_mov_b64 s[34:35], 0
	v_mov_b32_e32 v1, v0
	v_mov_b32_e32 v2, v0
	v_mov_b32_e32 v3, v0
	v_mov_b32_e32 v4, v0
	v_mov_b32_e32 v5, v0
	v_mov_b32_e32 v6, v0
	v_mov_b32_e32 v7, v0
	v_mov_b32_e32 v8, v0
	v_mov_b32_e32 v9, v0
	v_mov_b32_e32 v10, v0
	v_mov_b32_e32 v11, v0
	v_mov_b32_e32 v12, v0
	v_mov_b32_e32 v13, v0
	v_mov_b32_e32 v14, v0
	v_mov_b32_e32 v15, v0
	v_mov_b32_e32 v16, v0
	v_mov_b32_e32 v17, v0
	v_mov_b32_e32 v18, v0
	v_mov_b32_e32 v19, v0
	v_mov_b32_e32 v20, v0
	v_mov_b32_e32 v21, v0
	v_mov_b32_e32 v22, v0
	v_mov_b32_e32 v23, v0
	v_mov_b32_e32 v24, v0
	v_mov_b32_e32 v25, v0
	v_mov_b32_e32 v26, v0
	v_mov_b32_e32 v27, v0
	v_mov_b32_e32 v28, v0
	v_mov_b32_e32 v29, v0
	v_mov_b32_e32 v30, v0
	v_mov_b32_e32 v31, v0
	v_mov_b32_e32 v32, v0
	v_mov_b32_e32 v33, v0
	v_mov_b32_e32 v34, v0
	v_mov_b32_e32 v35, v0
	v_mov_b32_e32 v36, v0
	v_mov_b32_e32 v37, v0
	v_mov_b32_e32 v38, v0
	v_mov_b32_e32 v39, v0
	v_mov_b32_e32 v40, v0
	v_mov_b32_e32 v41, v0
	v_mov_b32_e32 v42, v0
	v_mov_b32_e32 v43, v0
	v_mov_b32_e32 v44, v0
	v_mov_b32_e32 v45, v0
	v_mov_b32_e32 v46, v0
	v_mov_b32_e32 v47, v0
	v_mov_b32_e32 v48, v0
	v_mov_b32_e32 v49, v0
	v_mov_b32_e32 v50, v0
	v_mov_b32_e32 v51, v0
	v_mov_b32_e32 v52, v0
	v_mov_b32_e32 v53, v0
	v_mov_b32_e32 v54, v0
	v_mov_b32_e32 v55, v0
	v_mov_b32_e32 v56, v0
	v_mov_b32_e32 v57, v0
	v_mov_b32_e32 v58, v0
	v_mov_b32_e32 v59, v0
	v_mov_b32_e32 v60, v0
	v_mov_b32_e32 v61, v0
	v_mov_b32_e32 v62, v0
	v_mov_b32_e32 v63, v0
	v_mov_b32_e32 v64, v0
	v_mov_b32_e32 v65, v0
	v_mov_b32_e32 v66, v0
	v_mov_b32_e32 v67, v0
	v_mov_b32_e32 v68, v0
	v_mov_b32_e32 v69, v0
	v_mov_b32_e32 v70, v0
	v_mov_b32_e32 v71, v0
	v_mov_b32_e32 v72, v0
	v_mov_b32_e32 v73, v0
	v_mov_b32_e32 v74, v0
	v_mov_b32_e32 v75, v0
	v_mov_b32_e32 v76, v0
	v_mov_b32_e32 v77, v0
	v_mov_b32_e32 v78, v0
	v_mov_b32_e32 v79, v0
	v_mov_b32_e32 v80, v0
	v_mov_b32_e32 v81, v0
	v_mov_b32_e32 v82, v0
	v_mov_b32_e32 v83, v0
	v_mov_b32_e32 v84, v0
	v_mov_b32_e32 v85, v0
	v_mov_b32_e32 v86, v0
	v_mov_b32_e32 v87, v0
	v_mov_b32_e32 v88, v0
	v_mov_b32_e32 v89, v0
	v_mov_b32_e32 v90, v0
	v_mov_b32_e32 v91, v0
	v_mov_b32_e32 v92, v0
	v_mov_b32_e32 v93, v0
	v_mov_b32_e32 v94, v0
	v_mov_b32_e32 v95, v0
	v_mov_b32_e32 v96, v0
	v_mov_b32_e32 v97, v0
	v_mov_b32_e32 v98, v0
	v_mov_b32_e32 v99, v0
	v_mov_b32_e32 v100, v0
	v_mov_b32_e32 v101, v0
	v_mov_b32_e32 v102, v0
	v_mov_b32_e32 v103, v0
	v_mov_b32_e32 v104, v0
	v_mov_b32_e32 v105, v0
	v_mov_b32_e32 v106, v0
	v_mov_b32_e32 v107, v0
	v_mov_b32_e32 v108, v0
	v_mov_b32_e32 v109, v0
	v_mov_b32_e32 v110, v0
	v_mov_b32_e32 v111, v0
	v_mov_b32_e32 v112, v0
	v_mov_b32_e32 v113, v0
	v_mov_b32_e32 v114, v0
	v_mov_b32_e32 v115, v0
	v_mov_b32_e32 v116, v0
	v_mov_b32_e32 v117, v0
	v_mov_b32_e32 v118, v0
	v_mov_b32_e32 v119, v0
	v_mov_b32_e32 v120, v0
	v_mov_b32_e32 v121, v0
	v_mov_b32_e32 v122, v0
	v_mov_b32_e32 v123, v0
	v_mov_b32_e32 v124, v0
	v_mov_b32_e32 v125, v0
	v_mov_b32_e32 v126, v0
	v_mov_b32_e32 v127, v0
	s_and_b32 s53, s43, 0x10000
	s_xor_b32 s17, s53, 0x10000
	s_add_i32 s54, s38, s17
	v_add_u32_e32 v147, s53, v151
	v_or_b32_e32 v158, s53, v153
	v_add_u32_e32 v159, v147, v152
	v_add_u32_e32 v242, v158, v152
	s_ashr_i32 s19, s18, 31
	s_ashr_i32 s17, s16, 31
	ds_read_b128 v[226:229], v242 offset:32768
	ds_read_b128 v[230:233], v242 offset:34816
	ds_read_b128 v[234:237], v242 offset:36864
	ds_read_b128 v[238:241], v242 offset:38912
	ds_read_b128 v[154:157], v159
	ds_read_b128 v[166:169], v159 offset:2048
	ds_read_b128 v[170:173], v159 offset:4096
	ds_read_b128 v[174:177], v159 offset:6144
	ds_read_b128 v[178:181], v159 offset:8192
	ds_read_b128 v[196:199], v159 offset:10240
	ds_read_b128 v[200:203], v159 offset:12288
	ds_read_b128 v[204:207], v159 offset:14336
	s_mov_b32 m0, s54
	v_lshl_add_u64 v[244:245], v[144:145], 0, s[34:35]
	global_load_lds_dwordx4 v[244:245], off
	s_add_i32 m0, s54, 0x8000
	v_lshl_add_u64 v[244:245], v[142:143], 0, s[34:35]
	global_load_lds_dwordx4 v[244:245], off
	s_add_i32 m0, s54, 0x2000
	v_lshl_add_u64 v[244:245], s[18:19], 1, v[130:131]
	global_load_lds_dwordx4 v[244:245], off
	s_add_i32 m0, s54, 0xa000
	v_lshl_add_u64 v[244:245], s[16:17], 1, v[132:133]
	global_load_lds_dwordx4 v[244:245], off
	s_add_i32 m0, s54, 0x4000
	v_lshl_add_u64 v[244:245], v[140:141], 0, s[34:35]
	global_load_lds_dwordx4 v[244:245], off
	s_branch .Lkp_mid
; #define WAIT_V(n) asm volatile("s_waitcnt vmcnt(%0)" ::"n"(n) : "memory")
; #define COMPUTE(buf) do { _Pragma("unroll") for (int ks = 0; ks < KS; ++ks) KSTEP(buf, ks); } while (0)
; __device__ __forceinline__ void gemm_tile(const TileDesc& d, const TileDesc& dn, bool has_next, bool k0_pending) {
;     ...
;   const int nt = K / BK;
;   const bool pf_in_loop = has_next && d.kind != EPI_GATE;
;   if (k0_pending) { WAIT_V(0); __syncthreads(); }
;   for (int t = 0; t < nt - 1; ++t) { int cur = t & 1;
;     GLDS_STAGE_OF(Ab, lda, Bb, ldb, voA, voB, cur ^ 1, t + 1);
;     COMPUTE(cur);
;     WAIT_V(0); __syncthreads(); }
.LBB0_388:
	s_and_b32 s53, s43, 0x10000
	s_xor_b32 s17, s53, 0x10000
	s_add_i32 s54, s38, s17
	v_add_u32_e32 v147, s53, v151
	v_or_b32_e32 v158, s53, v153
	v_add_u32_e32 v159, v147, v152
	v_add_u32_e32 v242, v158, v152
	s_ashr_i32 s19, s18, 31
	s_ashr_i32 s17, s16, 31
	ds_read_b128 v[226:229], v242 offset:32768
	ds_read_b128 v[230:233], v242 offset:34816
	ds_read_b128 v[234:237], v242 offset:36864
	ds_read_b128 v[238:241], v242 offset:38912
	ds_read_b128 v[154:157], v159
	ds_read_b128 v[166:169], v159 offset:2048
	ds_read_b128 v[170:173], v159 offset:4096
	s_setprio 1
	v_mfma_f32_16x16x32_bf16 v[76:79], v[208:211], v[174:177], v[76:79]
	v_mfma_f32_16x16x32_bf16 v[72:75], v[212:215], v[174:177], v[72:75]
	v_mfma_f32_16x16x32_bf16 v[68:71], v[216:219], v[174:177], v[68:71]
	v_mfma_f32_16x16x32_bf16 v[64:67], v[220:223], v[174:177], v[64:67]
	ds_read_b128 v[174:177], v159 offset:6144
	s_mov_b32 m0, s54
	v_lshl_add_u64 v[244:245], v[144:145], 0, s[34:35]
	global_load_lds_dwordx4 v[244:245], off
	v_mfma_f32_16x16x32_bf16 v[60:63], v[208:211], v[178:181], v[60:63]
	v_mfma_f32_16x16x32_bf16 v[56:59], v[212:215], v[178:181], v[56:59]
	v_mfma_f32_16x16x32_bf16 v[52:55], v[216:219], v[178:181], v[52:55]
	v_mfma_f32_16x16x32_bf16 v[48:51], v[220:223], v[178:181], v[48:51]
	ds_read_b128 v[178:181], v159 offset:8192
	s_add_i32 m0, s54, 0x8000
	v_lshl_add_u64 v[244:245], v[142:143], 0, s[34:35]
	global_load_lds_dwordx4 v[244:245], off
	v_mfma_f32_16x16x32_bf16 v[44:47], v[208:211], v[196:199], v[44:47]
	v_mfma_f32_16x16x32_bf16 v[40:43], v[212:215], v[196:199], v[40:43]
	v_mfma_f32_16x16x32_bf16 v[36:39], v[216:219], v[196:199], v[36:39]
	v_mfma_f32_16x16x32_bf16 v[32:35], v[220:223], v[196:199], v[32:35]
	ds_read_b128 v[196:199], v159 offset:10240
	s_add_i32 m0, s54, 0x2000
	v_lshl_add_u64 v[244:245], s[18:19], 1, v[130:131]
	global_load_lds_dwordx4 v[244:245], off
	v_mfma_f32_16x16x32_bf16 v[28:31], v[208:211], v[200:203], v[28:31]
	v_mfma_f32_16x16x32_bf16 v[24:27], v[212:215], v[200:203], v[24:27]
	v_mfma_f32_16x16x32_bf16 v[20:23], v[216:219], v[200:203], v[20:23]
	v_mfma_f32_16x16x32_bf16 v[16:19], v[220:223], v[200:203], v[16:19]
	ds_read_b128 v[200:203], v159 offset:12288
	s_add_i32 m0, s54, 0xa000
	v_lshl_add_u64 v[244:245], s[16:17], 1, v[132:133]
	global_load_lds_dwordx4 v[244:245], off
	v_mfma_f32_16x16x32_bf16 v[12:15], v[208:211], v[204:207], v[12:15]
	v_mfma_f32_16x16x32_bf16 v[8:11], v[212:215], v[204:207], v[8:11]
	v_mfma_f32_16x16x32_bf16 v[4:7], v[216:219], v[204:207], v[4:7]
	v_mfma_f32_16x16x32_bf16 v[0:3], v[220:223], v[204:207], v[0:3]
	ds_read_b128 v[204:207], v159 offset:14336
	s_add_i32 m0, s54, 0x4000
	v_lshl_add_u64 v[244:245], v[140:141], 0, s[34:35]
	global_load_lds_dwordx4 v[244:245], off
.Lkp_mid:
	s_setprio 1
	s_waitcnt lgkmcnt(7)
	v_mfma_f32_16x16x32_bf16 v[124:127], v[226:229], v[154:157], v[124:127]
	v_mfma_f32_16x16x32_bf16 v[120:123], v[230:233], v[154:157], v[120:123]
	v_mfma_f32_16x16x32_bf16 v[116:119], v[234:237], v[154:157], v[116:119]
	v_mfma_f32_16x16x32_bf16 v[112:115], v[238:241], v[154:157], v[112:115]
	s_add_i32 m0, s54, 0xc000
	v_lshl_add_u64 v[244:245], v[138:139], 0, s[34:35]
	global_load_lds_dwordx4 v[244:245], off
	s_waitcnt lgkmcnt(6)
	v_mfma_f32_16x16x32_bf16 v[108:111], v[226:229], v[166:169], v[108:111]
	v_mfma_f32_16x16x32_bf16 v[104:107], v[230:233], v[166:169], v[104:107]
	v_mfma_f32_16x16x32_bf16 v[100:103], v[234:237], v[166:169], v[100:103]
	v_mfma_f32_16x16x32_bf16 v[96:99], v[238:241], v[166:169], v[96:99]
	s_add_i32 m0, s54, 0x6000
	v_lshl_add_u64 v[244:245], v[136:137], 0, s[34:35]
	global_load_lds_dwordx4 v[244:245], off
	s_waitcnt lgkmcnt(5)
	v_mfma_f32_16x16x32_bf16 v[92:95], v[226:229], v[170:173], v[92:95]
	v_mfma_f32_16x16x32_bf16 v[88:91], v[230:233], v[170:173], v[88:91]
	v_mfma_f32_16x16x32_bf16 v[84:87], v[234:237], v[170:173], v[84:87]
	v_mfma_f32_16x16x32_bf16 v[80:83], v[238:241], v[170:173], v[80:83]
	s_add_i32 m0, s54, 0xe000
	v_lshl_add_u64 v[244:245], v[134:135], 0, s[34:35]
	global_load_lds_dwordx4 v[244:245], off
	s_waitcnt lgkmcnt(4)
	v_mfma_f32_16x16x32_bf16 v[76:79], v[226:229], v[174:177], v[76:79]
	v_mfma_f32_16x16x32_bf16 v[72:75], v[230:233], v[174:177], v[72:75]
	v_mfma_f32_16x16x32_bf16 v[68:71], v[234:237], v[174:177], v[68:71]
	v_mfma_f32_16x16x32_bf16 v[64:67], v[238:241], v[174:177], v[64:67]
	s_waitcnt lgkmcnt(3)
	v_mfma_f32_16x16x32_bf16 v[60:63], v[226:229], v[178:181], v[60:63]
	v_mfma_f32_16x16x32_bf16 v[56:59], v[230:233], v[178:181], v[56:59]
	v_mfma_f32_16x16x32_bf16 v[52:55], v[234:237], v[178:181], v[52:55]
	v_mfma_f32_16x16x32_bf16 v[48:51], v[238:241], v[178:181], v[48:51]
	s_waitcnt lgkmcnt(2)
	v_mfma_f32_16x16x32_bf16 v[44:47], v[226:229], v[196:199], v[44:47]
	v_mfma_f32_16x16x32_bf16 v[40:43], v[230:233], v[196:199], v[40:43]
	v_mfma_f32_16x16x32_bf16 v[36:39], v[234:237], v[196:199], v[36:39]
	v_mfma_f32_16x16x32_bf16 v[32:35], v[238:241], v[196:199], v[32:35]
	s_waitcnt lgkmcnt(1)
	v_mfma_f32_16x16x32_bf16 v[28:31], v[226:229], v[200:203], v[28:31]
	v_mfma_f32_16x16x32_bf16 v[24:27], v[230:233], v[200:203], v[24:27]
	v_mfma_f32_16x16x32_bf16 v[20:23], v[234:237], v[200:203], v[20:23]
	v_mfma_f32_16x16x32_bf16 v[16:19], v[238:241], v[200:203], v[16:19]
	s_waitcnt lgkmcnt(0)
; #define WAIT_V(n) asm volatile("s_waitcnt vmcnt(%0)" ::"n"(n) : "memory")
; #define COMPUTE(buf) do { _Pragma("unroll") for (int ks = 0; ks < KS; ++ks) KSTEP(buf, ks); } while (0)
; __device__ __forceinline__ void gemm_tile(const TileDesc& d, const TileDesc& dn, bool has_next, bool k0_pending) {
;     ...
;   const int nt = K / BK;
;   const bool pf_in_loop = has_next && d.kind != EPI_GATE;
;   if (k0_pending) { WAIT_V(0); __syncthreads(); }
;   for (int t = 0; t < nt - 1; ++t) { int cur = t & 1;
;     GLDS_STAGE_OF(Ab, lda, Bb, ldb, voA, voB, cur ^ 1, t + 1);
;     COMPUTE(cur);
;     WAIT_V(0); __syncthreads(); }
;   if (pf_in_loop) GLDS_STAGE_OF(dn.A, dn.lda, dn.B, dn.ldb, nvoA, nvoB, 0, 0);
;   COMPUTE(1);
;   WAIT_V(0); __syncthreads();
	v_mfma_f32_16x16x32_bf16 v[12:15], v[226:229], v[204:207], v[12:15]
	v_mfma_f32_16x16x32_bf16 v[8:11], v[230:233], v[204:207], v[8:11]
	v_mfma_f32_16x16x32_bf16 v[4:7], v[234:237], v[204:207], v[4:7]
	v_mfma_f32_16x16x32_bf16 v[0:3], v[238:241], v[204:207], v[0:3]
	s_setprio 0
	v_add_u32_e32 v243, v147, v129
	v_add_u32_e32 v147, v158, v129
	ds_read_b128 v[208:211], v147 offset:32768
	ds_read_b128 v[212:215], v147 offset:34816
	ds_read_b128 v[216:219], v147 offset:36864
	ds_read_b128 v[220:223], v147 offset:38912
	ds_read_b128 v[154:157], v243
	ds_read_b128 v[166:169], v243 offset:2048
	ds_read_b128 v[170:173], v243 offset:4096
	ds_read_b128 v[174:177], v243 offset:6144
	ds_read_b128 v[178:181], v243 offset:8192
	ds_read_b128 v[196:199], v243 offset:10240
	ds_read_b128 v[200:203], v243 offset:12288
	ds_read_b128 v[204:207], v243 offset:14336
	s_setprio 1
	s_waitcnt lgkmcnt(7)
	v_mfma_f32_16x16x32_bf16 v[124:127], v[208:211], v[154:157], v[124:127]
	v_mfma_f32_16x16x32_bf16 v[120:123], v[212:215], v[154:157], v[120:123]
	v_mfma_f32_16x16x32_bf16 v[116:119], v[216:219], v[154:157], v[116:119]
	v_mfma_f32_16x16x32_bf16 v[112:115], v[220:223], v[154:157], v[112:115]
	s_waitcnt lgkmcnt(6)
	v_mfma_f32_16x16x32_bf16 v[108:111], v[208:211], v[166:169], v[108:111]
	v_mfma_f32_16x16x32_bf16 v[104:107], v[212:215], v[166:169], v[104:107]
	v_mfma_f32_16x16x32_bf16 v[100:103], v[216:219], v[166:169], v[100:103]
	v_mfma_f32_16x16x32_bf16 v[96:99], v[220:223], v[166:169], v[96:99]
	s_waitcnt lgkmcnt(5)
	v_mfma_f32_16x16x32_bf16 v[92:95], v[208:211], v[170:173], v[92:95]
	v_mfma_f32_16x16x32_bf16 v[88:91], v[212:215], v[170:173], v[88:91]
	v_mfma_f32_16x16x32_bf16 v[84:87], v[216:219], v[170:173], v[84:87]
	v_mfma_f32_16x16x32_bf16 v[80:83], v[220:223], v[170:173], v[80:83]
	s_setprio 0
	s_add_i32 s39, s39, -1
	s_add_i32 s16, s16, 64
	s_add_i32 s18, s18, 64
	s_add_i32 s43, s43, 0x10000
	s_add_u32 s34, s34, 0x80
	s_addc_u32 s35, s35, 0
	s_cmp_eq_u32 s39, 0
	s_waitcnt vmcnt(0) lgkmcnt(0)
	s_barrier
	s_cbranch_scc0 .LBB0_388
	v_mad_u64_u32 v[144:145], s[16:17], v146, s78, v[128:129]
	s_cmp_lg_u32 s90, 7
	s_cselect_b64 s[16:17], -1, 0
	s_and_b64 s[16:17], s[4:5], s[16:17]
	s_andn2_b64 vcc, exec, s[16:17]
	v_mad_u64_u32 v[146:147], s[16:17], v146, s42, v[128:129]
	s_cbranch_vccnz .LBB0_391
	v_mov_b32_e32 v145, v164
	v_lshlrev_b64 v[130:131], 1, v[144:145]
	s_mov_b32 m0, s38
	s_add_i32 s16, s38, 0x8000
	v_lshl_add_u64 v[132:133], s[20:21], 0, v[130:131]
	global_load_lds_dwordx4 v[132:133], off
	s_mov_b32 m0, s16
	s_lshl_b32 s16, s78, 6
	s_ashr_i32 s17, s16, 31
	s_lshl_b64 s[16:17], s[16:17], 1
	v_mov_b32_e32 v147, v164
	s_add_u32 s16, s20, s16
	v_lshlrev_b64 v[132:133], 1, v[146:147]
	s_addc_u32 s17, s21, s17
	s_lshl_b32 s18, s42, 6
	v_lshl_add_u64 v[134:135], s[22:23], 0, v[132:133]
	s_ashr_i32 s19, s18, 31
	global_load_lds_dwordx4 v[134:135], off
	s_add_i32 m0, s38, 0x2000
	s_lshl_b64 s[18:19], s[18:19], 1
	s_add_u32 s18, s22, s18
	v_lshl_add_u64 v[134:135], s[16:17], 0, v[130:131]
	s_addc_u32 s19, s23, s19
	s_ashr_i32 s79, s78, 31
	global_load_lds_dwordx4 v[134:135], off
	s_add_i32 m0, s38, 0xa000
	s_lshl_b64 s[34:35], s[78:79], 7
	s_add_u32 s16, s16, s34
	v_lshl_add_u64 v[134:135], s[18:19], 0, v[132:133]
	s_addc_u32 s17, s17, s35
	s_ashr_i32 s43, s42, 31
	global_load_lds_dwordx4 v[134:135], off
	s_add_i32 m0, s38, 0x4000
	s_lshl_b64 s[54:55], s[42:43], 7
	v_lshl_add_u64 v[134:135], s[16:17], 0, v[130:131]
	s_add_u32 s18, s18, s54
	global_load_lds_dwordx4 v[134:135], off
	s_addc_u32 s19, s19, s55
	s_add_i32 m0, s38, 0xc000
	v_lshl_add_u64 v[134:135], s[18:19], 0, v[132:133]
	s_add_u32 s16, s16, s34
	global_load_lds_dwordx4 v[134:135], off
	s_addc_u32 s17, s17, s35
	s_add_i32 m0, s38, 0x6000
	v_lshl_add_u64 v[130:131], s[16:17], 0, v[130:131]
	s_add_u32 s16, s18, s54
	s_addc_u32 s17, s19, s55
	global_load_lds_dwordx4 v[130:131], off
	v_lshl_add_u64 v[130:131], s[16:17], 0, v[132:133]
	s_add_i32 m0, s38, 0xe000
	s_nop 0
	global_load_lds_dwordx4 v[130:131], off
.LBB0_391:
	v_add_u32_e32 v128, 0x10000, v151
	v_or_b32_e32 v142, 0x18000, v153
	v_add_u32_e32 v143, v128, v152
	v_add_u32_e32 v242, v142, v152
	ds_read_b128 v[226:229], v242
	ds_read_b128 v[230:233], v242 offset:2048
	ds_read_b128 v[234:237], v242 offset:4096
	ds_read_b128 v[238:241], v242 offset:6144
	ds_read_b128 v[154:157], v143
	ds_read_b128 v[166:169], v143 offset:2048
	ds_read_b128 v[170:173], v143 offset:4096
	s_setprio 1
	v_mfma_f32_16x16x32_bf16 v[76:79], v[208:211], v[174:177], v[76:79]
	v_mfma_f32_16x16x32_bf16 v[72:75], v[212:215], v[174:177], v[72:75]
	v_mfma_f32_16x16x32_bf16 v[68:71], v[216:219], v[174:177], v[68:71]
	v_mfma_f32_16x16x32_bf16 v[64:67], v[220:223], v[174:177], v[64:67]
	ds_read_b128 v[174:177], v143 offset:6144
	v_mfma_f32_16x16x32_bf16 v[60:63], v[208:211], v[178:181], v[60:63]
	v_mfma_f32_16x16x32_bf16 v[56:59], v[212:215], v[178:181], v[56:59]
	v_mfma_f32_16x16x32_bf16 v[52:55], v[216:219], v[178:181], v[52:55]
	v_mfma_f32_16x16x32_bf16 v[48:51], v[220:223], v[178:181], v[48:51]
	ds_read_b128 v[178:181], v143 offset:8192
	v_mfma_f32_16x16x32_bf16 v[44:47], v[208:211], v[196:199], v[44:47]
	v_mfma_f32_16x16x32_bf16 v[40:43], v[212:215], v[196:199], v[40:43]
	v_mfma_f32_16x16x32_bf16 v[36:39], v[216:219], v[196:199], v[36:39]
	v_mfma_f32_16x16x32_bf16 v[32:35], v[220:223], v[196:199], v[32:35]
	ds_read_b128 v[196:199], v143 offset:10240
	v_mfma_f32_16x16x32_bf16 v[28:31], v[208:211], v[200:203], v[28:31]
	v_mfma_f32_16x16x32_bf16 v[24:27], v[212:215], v[200:203], v[24:27]
	v_mfma_f32_16x16x32_bf16 v[20:23], v[216:219], v[200:203], v[20:23]
	v_mfma_f32_16x16x32_bf16 v[16:19], v[220:223], v[200:203], v[16:19]
	ds_read_b128 v[200:203], v143 offset:12288
	v_mfma_f32_16x16x32_bf16 v[12:15], v[208:211], v[204:207], v[12:15]
	v_mfma_f32_16x16x32_bf16 v[8:11], v[212:215], v[204:207], v[8:11]
	v_mfma_f32_16x16x32_bf16 v[4:7], v[216:219], v[204:207], v[4:7]
	v_mfma_f32_16x16x32_bf16 v[0:3], v[220:223], v[204:207], v[0:3]
	ds_read_b128 v[204:207], v143 offset:14336
	s_setprio 1
	s_waitcnt lgkmcnt(7)
; #define WAIT_V(n) asm volatile("s_waitcnt vmcnt(%0)" ::"n"(n) : "memory")
; #define COMPUTE(buf) do { _Pragma("unroll") for (int ks = 0; ks < KS; ++ks) KSTEP(buf, ks); } while (0)
; __device__ __forceinline__ void gemm_tile(const TileDesc& d, const TileDesc& dn, bool has_next, bool k0_pending) {
;     ...
;   const int nt = K / BK;
;   const bool pf_in_loop = has_next && d.kind != EPI_GATE;
;   if (k0_pending) { WAIT_V(0); __syncthreads(); }
;   for (int t = 0; t < nt - 1; ++t) { int cur = t & 1;
;     GLDS_STAGE_OF(Ab, lda, Bb, ldb, voA, voB, cur ^ 1, t + 1);
;     COMPUTE(cur);
;     WAIT_V(0); __syncthreads(); }
;   if (pf_in_loop) GLDS_STAGE_OF(dn.A, dn.lda, dn.B, dn.ldb, nvoA, nvoB, 0, 0);
;   COMPUTE(1);
;   WAIT_V(0); __syncthreads();
;   unsigned xcr[32];
;   if (d.kind == EPI_GATE) {
; #pragma unroll
;     for (int q = 0; q < 2; ++q) {
;       const char* xl = g_shm + q * STAGE_B + wr * 16384 + fr * 128 + (((wc * 2 + (fq >> 1)) ^ ((fr >> 1) & 7)) << 4) + (fq & 1) * 8;
; #pragma unroll
;       for (int m = 0; m < 8; ++m) { uint2 w = *(const uint2*)(xl + m * 2048); xcr[q * 16 + m * 2] = w.x; xcr[q * 16 + m * 2 + 1] = w.y; } }
;     __syncthreads();
;     if (has_next) GLDS_STAGE_OF(dn.A, dn.lda, dn.B, dn.ldb, nvoA, nvoB, 0, 0);
;   } else {
; #pragma unroll
;     for (int i = 0; i < 32; ++i) xcr[i] = 0u;
	v_mfma_f32_16x16x32_bf16 v[124:127], v[226:229], v[154:157], v[124:127]
	v_mfma_f32_16x16x32_bf16 v[120:123], v[230:233], v[154:157], v[120:123]
	v_mfma_f32_16x16x32_bf16 v[116:119], v[234:237], v[154:157], v[116:119]
	v_mfma_f32_16x16x32_bf16 v[112:115], v[238:241], v[154:157], v[112:115]
	s_waitcnt lgkmcnt(6)
	v_mfma_f32_16x16x32_bf16 v[108:111], v[226:229], v[166:169], v[108:111]
	v_mfma_f32_16x16x32_bf16 v[104:107], v[230:233], v[166:169], v[104:107]
	v_mfma_f32_16x16x32_bf16 v[100:103], v[234:237], v[166:169], v[100:103]
	v_mfma_f32_16x16x32_bf16 v[96:99], v[238:241], v[166:169], v[96:99]
	s_waitcnt lgkmcnt(5)
	v_mfma_f32_16x16x32_bf16 v[92:95], v[226:229], v[170:173], v[92:95]
	v_mfma_f32_16x16x32_bf16 v[88:91], v[230:233], v[170:173], v[88:91]
	v_mfma_f32_16x16x32_bf16 v[84:87], v[234:237], v[170:173], v[84:87]
	v_mfma_f32_16x16x32_bf16 v[80:83], v[238:241], v[170:173], v[80:83]
	s_waitcnt lgkmcnt(4)
	v_mfma_f32_16x16x32_bf16 v[76:79], v[226:229], v[174:177], v[76:79]
	v_mfma_f32_16x16x32_bf16 v[72:75], v[230:233], v[174:177], v[72:75]
	v_mfma_f32_16x16x32_bf16 v[68:71], v[234:237], v[174:177], v[68:71]
	v_mfma_f32_16x16x32_bf16 v[64:67], v[238:241], v[174:177], v[64:67]
	s_waitcnt lgkmcnt(3)
	v_mfma_f32_16x16x32_bf16 v[60:63], v[226:229], v[178:181], v[60:63]
	v_mfma_f32_16x16x32_bf16 v[56:59], v[230:233], v[178:181], v[56:59]
	v_mfma_f32_16x16x32_bf16 v[52:55], v[234:237], v[178:181], v[52:55]
	v_mfma_f32_16x16x32_bf16 v[48:51], v[238:241], v[178:181], v[48:51]
	s_waitcnt lgkmcnt(2)
	v_mfma_f32_16x16x32_bf16 v[44:47], v[226:229], v[196:199], v[44:47]
	v_mfma_f32_16x16x32_bf16 v[40:43], v[230:233], v[196:199], v[40:43]
	v_mfma_f32_16x16x32_bf16 v[36:39], v[234:237], v[196:199], v[36:39]
	v_mfma_f32_16x16x32_bf16 v[32:35], v[238:241], v[196:199], v[32:35]
	s_waitcnt lgkmcnt(1)
	v_mfma_f32_16x16x32_bf16 v[28:31], v[226:229], v[200:203], v[28:31]
	v_mfma_f32_16x16x32_bf16 v[24:27], v[230:233], v[200:203], v[24:27]
	v_mfma_f32_16x16x32_bf16 v[20:23], v[234:237], v[200:203], v[20:23]
	v_mfma_f32_16x16x32_bf16 v[16:19], v[238:241], v[200:203], v[16:19]
	s_waitcnt lgkmcnt(0)
	v_mfma_f32_16x16x32_bf16 v[12:15], v[226:229], v[204:207], v[12:15]
	v_mfma_f32_16x16x32_bf16 v[8:11], v[230:233], v[204:207], v[8:11]
	v_mfma_f32_16x16x32_bf16 v[4:7], v[234:237], v[204:207], v[4:7]
	v_mfma_f32_16x16x32_bf16 v[0:3], v[238:241], v[204:207], v[0:3]
	s_setprio 0
	v_add_u32_e32 v128, v128, v129
	v_add_u32_e32 v143, v142, v129
	ds_read_b128 v[208:211], v143
	ds_read_b128 v[212:215], v143 offset:2048
	ds_read_b128 v[216:219], v143 offset:4096
	ds_read_b128 v[220:223], v143 offset:6144
	ds_read_b128 v[154:157], v128
	ds_read_b128 v[166:169], v128 offset:2048
	ds_read_b128 v[170:173], v128 offset:4096
	ds_read_b128 v[174:177], v128 offset:6144
	ds_read_b128 v[178:181], v128 offset:8192
	ds_read_b128 v[196:199], v128 offset:10240
	ds_read_b128 v[200:203], v128 offset:12288
	ds_read_b128 v[204:207], v128 offset:14336
	s_setprio 1
	s_waitcnt lgkmcnt(7)
	v_mfma_f32_16x16x32_bf16 v[124:127], v[208:211], v[154:157], v[124:127]
	v_mfma_f32_16x16x32_bf16 v[120:123], v[212:215], v[154:157], v[120:123]
	v_mfma_f32_16x16x32_bf16 v[116:119], v[216:219], v[154:157], v[116:119]
	v_mfma_f32_16x16x32_bf16 v[112:115], v[220:223], v[154:157], v[112:115]
	s_waitcnt lgkmcnt(6)
	v_mfma_f32_16x16x32_bf16 v[108:111], v[208:211], v[166:169], v[108:111]
	v_mfma_f32_16x16x32_bf16 v[104:107], v[212:215], v[166:169], v[104:107]
	v_mfma_f32_16x16x32_bf16 v[100:103], v[216:219], v[166:169], v[100:103]
	v_mfma_f32_16x16x32_bf16 v[96:99], v[220:223], v[166:169], v[96:99]
	s_waitcnt lgkmcnt(5)
	v_mfma_f32_16x16x32_bf16 v[92:95], v[208:211], v[170:173], v[92:95]
	v_mfma_f32_16x16x32_bf16 v[88:91], v[212:215], v[170:173], v[88:91]
	v_mfma_f32_16x16x32_bf16 v[84:87], v[216:219], v[170:173], v[84:87]
	v_mfma_f32_16x16x32_bf16 v[80:83], v[220:223], v[170:173], v[80:83]
	s_waitcnt lgkmcnt(4)
	v_mfma_f32_16x16x32_bf16 v[76:79], v[208:211], v[174:177], v[76:79]
	v_mfma_f32_16x16x32_bf16 v[72:75], v[212:215], v[174:177], v[72:75]
	v_mfma_f32_16x16x32_bf16 v[68:71], v[216:219], v[174:177], v[68:71]
	v_mfma_f32_16x16x32_bf16 v[64:67], v[220:223], v[174:177], v[64:67]
	s_waitcnt lgkmcnt(3)
	v_mfma_f32_16x16x32_bf16 v[60:63], v[208:211], v[178:181], v[60:63]
	v_mfma_f32_16x16x32_bf16 v[56:59], v[212:215], v[178:181], v[56:59]
	v_mfma_f32_16x16x32_bf16 v[52:55], v[216:219], v[178:181], v[52:55]
	v_mfma_f32_16x16x32_bf16 v[48:51], v[220:223], v[178:181], v[48:51]
	s_waitcnt lgkmcnt(2)
	v_mfma_f32_16x16x32_bf16 v[44:47], v[208:211], v[196:199], v[44:47]
	v_mfma_f32_16x16x32_bf16 v[40:43], v[212:215], v[196:199], v[40:43]
	v_mfma_f32_16x16x32_bf16 v[36:39], v[216:219], v[196:199], v[36:39]
	v_mfma_f32_16x16x32_bf16 v[32:35], v[220:223], v[196:199], v[32:35]
	s_waitcnt lgkmcnt(1)
	v_mfma_f32_16x16x32_bf16 v[28:31], v[208:211], v[200:203], v[28:31]
	v_mfma_f32_16x16x32_bf16 v[24:27], v[212:215], v[200:203], v[24:27]
	v_mfma_f32_16x16x32_bf16 v[20:23], v[216:219], v[200:203], v[20:23]
	v_mfma_f32_16x16x32_bf16 v[16:19], v[220:223], v[200:203], v[16:19]
	s_waitcnt lgkmcnt(0)
	v_mfma_f32_16x16x32_bf16 v[12:15], v[208:211], v[204:207], v[12:15]
	v_mfma_f32_16x16x32_bf16 v[8:11], v[212:215], v[204:207], v[8:11]
	v_mfma_f32_16x16x32_bf16 v[4:7], v[216:219], v[204:207], v[4:7]
	v_mfma_f32_16x16x32_bf16 v[0:3], v[220:223], v[204:207], v[0:3]
	s_setprio 0
	s_waitcnt vmcnt(0)
	s_cmp_eq_u32 s90, 7
	v_mov_b32_e32 v166, 0
	s_cselect_b64 s[54:55], -1, 0
	s_cmp_lg_u32 s90, 7
	v_mov_b32_e32 v167, 0
	v_mov_b32_e32 v168, 0
	v_mov_b32_e32 v169, 0
	v_mov_b32_e32 v170, 0
	v_mov_b32_e32 v171, 0
	v_mov_b32_e32 v172, 0
	v_mov_b32_e32 v173, 0
	v_mov_b32_e32 v174, 0
	v_mov_b32_e32 v175, 0
	v_mov_b32_e32 v176, 0
	v_mov_b32_e32 v177, 0
	v_mov_b32_e32 v178, 0
	v_mov_b32_e32 v179, 0
	v_mov_b32_e32 v180, 0
	v_mov_b32_e32 v181, 0
	v_mov_b32_e32 v130, 0
	v_mov_b32_e32 v131, 0
	v_mov_b32_e32 v128, 0
	v_mov_b32_e32 v129, 0
	v_mov_b32_e32 v134, 0
	v_mov_b32_e32 v135, 0
	v_mov_b32_e32 v132, 0
	v_mov_b32_e32 v133, 0
	v_mov_b32_e32 v138, 0
	v_mov_b32_e32 v139, 0
	v_mov_b32_e32 v136, 0
	v_mov_b32_e32 v137, 0
	v_mov_b32_e32 v142, 0
	v_mov_b32_e32 v143, 0
	v_mov_b32_e32 v140, 0
	v_mov_b32_e32 v141, 0
	s_waitcnt vmcnt(0)
	s_barrier
; __device__ __forceinline__ void gemm_tile(const TileDesc& d, const TileDesc& dn, bool has_next, bool k0_pending) {
;     ...
;   if (d.kind == EPI_GATE) {
; #pragma unroll
;     for (int q = 0; q < 2; ++q) {
;       const char* xl = g_shm + q * STAGE_B + wr * 16384 + fr * 128 + (((wc * 2 + (fq >> 1)) ^ ((fr >> 1) & 7)) << 4) + (fq & 1) * 8;
; #pragma unroll
;       for (int m = 0; m < 8; ++m) { uint2 w = *(const uint2*)(xl + m * 2048); xcr[q * 16 + m * 2] = w.x; xcr[q * 16 + m * 2 + 1] = w.y; } }
;     __syncthreads();
;     if (has_next) GLDS_STAGE_OF(dn.A, dn.lda, dn.B, dn.ldb, nvoA, nvoB, 0, 0);
	s_cbranch_scc1 .LBB0_394
	v_lshlrev_b32_e32 v129, 1, v195
	v_lshrrev_b32_e32 v130, 5, v148
	v_bitop3_b32 v129, v129, v149, v130 bitop3:0x36
	v_lshlrev_b32_e32 v130, 3, v193
	v_add_u32_e32 v128, v151, v150
	v_lshlrev_b32_e32 v129, 4, v129
	v_and_b32_e32 v130, 8, v130
	v_add3_u32 v145, v128, v129, v130
	v_add_u32_e32 v147, 0x10000, v145
	ds_read2st64_b64 v[140:143], v145 offset1:4
	ds_read2st64_b64 v[136:139], v145 offset0:8 offset1:12
	ds_read2st64_b64 v[132:135], v145 offset0:16 offset1:20
	ds_read2st64_b64 v[128:131], v145 offset0:24 offset1:28
	v_add_u32_e32 v148, 0x10800, v145
	v_add_u32_e32 v149, 0x11000, v145
	v_add_u32_e32 v150, 0x11800, v145
	ds_read_b64 v[180:181], v147
	ds_read_b64 v[178:179], v148
	ds_read_b64 v[176:177], v149
	ds_read_b64 v[174:175], v150
	v_add_u32_e32 v147, 0x12000, v145
	v_add_u32_e32 v148, 0x12800, v145
	v_add_u32_e32 v149, 0x13000, v145
	v_add_u32_e32 v145, 0x13800, v145
	ds_read_b64 v[172:173], v147
	ds_read_b64 v[170:171], v148
	ds_read_b64 v[168:169], v149
	ds_read_b64 v[166:167], v145
	s_andn2_b64 vcc, exec, s[4:5]
	s_waitcnt lgkmcnt(0)
	s_barrier
	s_cbranch_vccnz .LBB0_394
	v_mov_b32_e32 v145, v164
	v_lshlrev_b64 v[144:145], 1, v[144:145]
	s_mov_b32 m0, s38
	s_add_i32 s4, s38, 0x8000
	v_lshl_add_u64 v[148:149], s[20:21], 0, v[144:145]
	global_load_lds_dwordx4 v[148:149], off
	s_mov_b32 m0, s4
	s_lshl_b32 s4, s78, 6
	s_ashr_i32 s5, s4, 31
	s_lshl_b64 s[4:5], s[4:5], 1
	v_mov_b32_e32 v147, v164
	s_add_u32 s4, s20, s4
	v_lshlrev_b64 v[146:147], 1, v[146:147]
	s_addc_u32 s5, s21, s5
	s_lshl_b32 s16, s42, 6
	v_lshl_add_u64 v[148:149], s[22:23], 0, v[146:147]
	s_ashr_i32 s17, s16, 31
	global_load_lds_dwordx4 v[148:149], off
	s_add_i32 m0, s38, 0x2000
	s_lshl_b64 s[16:17], s[16:17], 1
	s_add_u32 s16, s22, s16
	v_lshl_add_u64 v[148:149], s[4:5], 0, v[144:145]
	s_addc_u32 s17, s23, s17
	s_ashr_i32 s79, s78, 31
	global_load_lds_dwordx4 v[148:149], off
	s_add_i32 m0, s38, 0xa000
	s_lshl_b64 s[18:19], s[78:79], 7
	s_add_u32 s4, s4, s18
	v_lshl_add_u64 v[148:149], s[16:17], 0, v[146:147]
	s_addc_u32 s5, s5, s19
	s_ashr_i32 s43, s42, 31
	global_load_lds_dwordx4 v[148:149], off
	s_add_i32 m0, s38, 0x4000
	s_lshl_b64 s[34:35], s[42:43], 7
	v_lshl_add_u64 v[148:149], s[4:5], 0, v[144:145]
	s_add_u32 s16, s16, s34
	global_load_lds_dwordx4 v[148:149], off
	s_addc_u32 s17, s17, s35
	s_add_i32 m0, s38, 0xc000
	v_lshl_add_u64 v[148:149], s[16:17], 0, v[146:147]
	s_add_u32 s4, s4, s18
	global_load_lds_dwordx4 v[148:149], off
	s_addc_u32 s5, s5, s19
	s_add_i32 m0, s38, 0x6000
	v_lshl_add_u64 v[144:145], s[4:5], 0, v[144:145]
	s_add_u32 s4, s16, s34
	s_addc_u32 s5, s17, s35
	global_load_lds_dwordx4 v[144:145], off
	v_lshl_add_u64 v[144:145], s[4:5], 0, v[146:147]
	s_add_i32 m0, s38, 0xe000
	s_nop 0
	global_load_lds_dwordx4 v[144:145], off

; __global__ void __launch_bounds__(512) fwd_megakernel(Params p_unused) {
;   cg::grid_group grid = cg::this_grid();
;   KP pp = (KP)__builtin_amdgcn_kernarg_segment_ptr();
;   grid.sync();
;     ...
; #pragma clang loop unroll(disable)
;   for (int step = 0; step < DEPTH * NCHUNK * 10; ++step) {
;     const int lc = step / 10, phi = step - lc * 10, ph = phi < 4 ? phi : phi + 1, l = lc >> 2, c = lc & 3;
;     if (ph == 0 && c > 0) continue;
;     switch (ph) {
;       case 0: if (l > 0) phase_resid(pp, l - 1, NCHUNK - 1); phase_convert(pp, l); rows_mem(pp, l); phase_norm(pp, l, 0); break;
;       case 2: phase2(pp, l, c); break;
;       case 4: phase4a(pp); break;
;       case 5: phase4b(pp, c); break;
;       case 6: phase4c(pp, l); break;
;       case 8: phase6(pp, l, c); break;
;       default: break;
;     }
;     const int nt = gemm_ntiles(ph, c);
;     { int v = blockIdx.x;
;       TileDesc d, dn;
;       bool pend = true;
;       if (v < nt) { make_desc(pp, ph, l, c, v, d); __syncthreads(); gemm_prefetch(d); }
;       if (ph == 2 && c > 0) phase_resid(pp, l, c - 1);
;       if (ph == 10 && c + 1 < NCHUNK) phase_norm(pp, l, c + 1);
; #pragma clang loop unroll(disable)
;       while (v < nt) {
;         const int vn = v + gridDim.x; const bool hn = vn < nt;
;         if (hn) make_desc(pp, ph, l, c, vn, dn); else dn = d;
;         gemm_tile(d, dn, hn, pend);
;         pend = (d.kind == EPI_GATE);
;         d = dn; v = vn; } }
;     xcd_barrier(xb);
;   }
;   phase_final(pp);
; }
	.amdhsa_kernel _Z14fwd_megakernel6Params
		.amdhsa_group_segment_fixed_size 139264
		.amdhsa_private_segment_fixed_size 0
		.amdhsa_kernarg_size 456
		.amdhsa_user_sgpr_count 2
		.amdhsa_user_sgpr_dispatch_ptr 0
		.amdhsa_user_sgpr_queue_ptr 0
		.amdhsa_user_sgpr_kernarg_segment_ptr 1
		.amdhsa_user_sgpr_dispatch_id 0
		.amdhsa_user_sgpr_kernarg_preload_length 0
		.amdhsa_user_sgpr_kernarg_preload_offset 0
		.amdhsa_user_sgpr_private_segment_size 0
		.amdhsa_uses_dynamic_stack 0
		.amdhsa_enable_private_segment 0
		.amdhsa_system_sgpr_workgroup_id_x 1
		.amdhsa_system_sgpr_workgroup_id_y 0
		.amdhsa_system_sgpr_workgroup_id_z 0
		.amdhsa_system_sgpr_workgroup_info 0
		.amdhsa_system_vgpr_workitem_id 2
		.amdhsa_next_free_vgpr 246
		.amdhsa_next_free_sgpr 100
		.amdhsa_accum_offset 248
		.amdhsa_reserve_vcc 1
		.amdhsa_float_round_mode_32 0
		.amdhsa_float_round_mode_16_64 0
		.amdhsa_float_denorm_mode_32 3
		.amdhsa_float_denorm_mode_16_64 3
		.amdhsa_dx10_clamp 1
		.amdhsa_ieee_mode 1
		.amdhsa_fp16_overflow 0
		.amdhsa_tg_split 0
		.amdhsa_exception_fp_ieee_invalid_op 0
		.amdhsa_exception_fp_denorm_src 0
		.amdhsa_exception_fp_ieee_div_zero 0
		.amdhsa_exception_fp_ieee_overflow 0
		.amdhsa_exception_fp_ieee_underflow 0
		.amdhsa_exception_fp_ieee_inexact 0
		.amdhsa_exception_int_div_zero 0
	.end_amdhsa_kernel

; __global__ void __launch_bounds__(512) fwd_megakernel(Params p_unused) {
;   cg::grid_group grid = cg::this_grid();
;   KP pp = (KP)__builtin_amdgcn_kernarg_segment_ptr();
;   grid.sync();
;     ...
; #pragma clang loop unroll(disable)
;   for (int step = 0; step < DEPTH * NCHUNK * 10; ++step) {
;     const int lc = step / 10, phi = step - lc * 10, ph = phi < 4 ? phi : phi + 1, l = lc >> 2, c = lc & 3;
;     if (ph == 0 && c > 0) continue;
;     switch (ph) {
;       case 0: if (l > 0) phase_resid(pp, l - 1, NCHUNK - 1); phase_convert(pp, l); rows_mem(pp, l); phase_norm(pp, l, 0); break;
;       case 2: phase2(pp, l, c); break;
;       case 4: phase4a(pp); break;
;       case 5: phase4b(pp, c); break;
;       case 6: phase4c(pp, l); break;
;       case 8: phase6(pp, l, c); break;
;       default: break;
;     }
;     const int nt = gemm_ntiles(ph, c);
;     { int v = blockIdx.x;
;       TileDesc d, dn;
;       bool pend = true;
;       if (v < nt) { make_desc(pp, ph, l, c, v, d); __syncthreads(); gemm_prefetch(d); }
;       if (ph == 2 && c > 0) phase_resid(pp, l, c - 1);
;       if (ph == 10 && c + 1 < NCHUNK) phase_norm(pp, l, c + 1);
; #pragma clang loop unroll(disable)
;       while (v < nt) {
;         const int vn = v + gridDim.x; const bool hn = vn < nt;
;         if (hn) make_desc(pp, ph, l, c, vn, dn); else dn = d;
;         gemm_tile(d, dn, hn, pend);
;         pend = (d.kind == EPI_GATE);
;         d = dn; v = vn; } }
;     xcd_barrier(xb);
;   }
;   phase_final(pp);
; }
amdhsa.kernels:
  - .agpr_count:     0
    .args:
      - .offset:         0
        .size:           200
        .value_kind:     by_value
      - .offset:         200
        .size:           4
        .value_kind:     hidden_block_count_x
      - .offset:         204
        .size:           4
        .value_kind:     hidden_block_count_y
      - .offset:         208
        .size:           4
        .value_kind:     hidden_block_count_z
      - .offset:         212
        .size:           2
        .value_kind:     hidden_group_size_x
      - .offset:         214
        .size:           2
        .value_kind:     hidden_group_size_y
      - .offset:         216
        .size:           2
        .value_kind:     hidden_group_size_z
      - .offset:         218
        .size:           2
        .value_kind:     hidden_remainder_x
      - .offset:         220
        .size:           2
        .value_kind:     hidden_remainder_y
      - .offset:         222
        .size:           2
        .value_kind:     hidden_remainder_z
      - .offset:         240
        .size:           8
        .value_kind:     hidden_global_offset_x
      - .offset:         248
        .size:           8
        .value_kind:     hidden_global_offset_y
      - .offset:         256
        .size:           8
        .value_kind:     hidden_global_offset_z
      - .offset:         264
        .size:           2
        .value_kind:     hidden_grid_dims
      - .offset:         288
        .size:           8
        .value_kind:     hidden_multigrid_sync_arg
    .group_segment_fixed_size: 139264
    .kernarg_segment_align: 8
    .kernarg_segment_size: 456
    .language:       OpenCL C
    .language_version:
      - 2
      - 0
    .max_flat_workgroup_size: 512
    .name:           _Z14fwd_megakernel6Params
    .private_segment_fixed_size: 0
    .sgpr_count:     106
    .sgpr_spill_count: 125
    .symbol:         _Z14fwd_megakernel6Params.kd
    .uniform_work_group_size: 1
    .uses_dynamic_stack: false
    .vgpr_count:     246
    .vgpr_spill_count: 0
    .wavefront_size: 64
